# speedup vs baseline: 1.1063x; 1.0032x over previous
; #define WAITV8(n) asm volatile("s_waitcnt vmcnt(" #n ")" ::: "memory")
; #define BAR8 __builtin_amdgcn_s_barrier()
; template <class Epi>
; DEV void gemm_tile8(char* shm, const u16* __restrict__ A, const u16* __restrict__ Bt, int K, int brow, int bcol, Epi& epi) {
;     ...
;   WAITV8(0);
;   STAGE8(SB8(0, 0), Bt, bcol, 0); STAGE8(SA8(0, 0), A, brow, 0);
;   STAGE8(SB8(0, 1), Bt, bcol + HALF, 0); STAGE8(SA8(0, 1), A, brow + HALF, 0);
;   if (wrs == 1) BAR8;
; DEV void rstd_tile_begin(const float* ss, int brow, char* shm, int tid) {
;   if (tid < 256 && brow + tid < TH) {
;     const float4* sp = (const float4*)(ss + (long)(brow + tid) * 16);
;     const float4 a = sp[0], b = sp[1], c = sp[2], d = sp[3];
;     const float t = (a.x + a.y + a.z + a.w) + (b.x + b.y + b.z + b.w) + (c.x + c.y + c.z + c.w) + (d.x + d.y + d.z + d.w);
;     ((float*)(shm + 131072))[(brow + tid) & 255] = rsqrtf(t * (1.f / 1024.f) + 1e-6f);
;   }
; }
.LBB0_462:
	s_and_b64 vcc, exec, s[10:11]
	s_cbranch_vccz .LBB0_451
	s_waitcnt vmcnt(3)
	v_mov_b32_e32 v8, v197
	s_movk_i32 s7, 0x100
	s_nop 0
	v_cmp_gt_i32_e32 vcc, s7, v8
	v_add_u32_e32 v0, s22, v8
	s_movk_i32 s7, 0x4000
	v_ashrrev_i32_e32 v6, 6, v8
	v_ashrrev_i32_e32 v7, 8, v8
	v_cmp_gt_i32_e64 s[10:11], s7, v0
	v_readfirstlane_b32 s45, v7
	v_readfirstlane_b32 s23, v6
	v_add_u32_e32 v32, s22, v8
	v_lshlrev_b32_e32 v0, 4, v8
	v_and_b32_e32 v1, 32, v8
	v_lshrrev_b32_e32 v2, 31, v6
	v_bitop3_b32 v0, v0, v1, 48 bitop3:0x6c
	v_add_u32_e32 v2, v6, v2
	v_lshrrev_b32_e32 v10, 1, v0
	v_lshlrev_b32_e32 v0, 8, v8
	v_ashrrev_i32_e32 v9, 1, v2
	v_and_b32_e32 v2, 0x7fffffe, v2
	v_and_b32_e32 v11, 0x3c00, v0
	v_sub_u32_e32 v2, v6, v2
	v_lshl_or_b32 v0, v9, 14, v11
	v_lshl_add_u32 v0, v2, 5, v0
	s_ashr_i32 s7, s6, 31
	v_or_b32_e32 v0, v0, v10
	s_lshl_b64 s[24:25], s[6:7], 11
	s_add_u32 s10, s30, s24
	v_ashrrev_i32_e32 v1, 31, v0
	s_addc_u32 s11, s31, s25
	s_waitcnt vmcnt(2)
	v_lshlrev_b64 v[12:13], 1, v[0:1]
	s_lshl_b32 s7, s23, 10
	s_ashr_i32 s23, s22, 31
	v_lshl_add_u64 v[0:1], s[10:11], 0, v[12:13]
	s_add_i32 s48, s7, 0x10000
	s_add_i32 s54, s7, 0x12000
	s_lshl_b64 s[10:11], s[22:23], 11
	s_waitcnt vmcnt(0)
	s_mov_b32 m0, s48
	s_mov_b64 s[84:85], 0x20000
	s_add_u32 s70, s26, s10
	global_load_lds_dwordx4 v[0:1], off
	v_lshl_add_u64 v[2:3], v[0:1], 0, s[84:85]
	s_mov_b32 m0, s54
	s_addc_u32 s71, s27, s11
	global_load_lds_dwordx4 v[2:3], off
	v_lshl_add_u64 v[2:3], s[70:71], 0, v[12:13]
	s_or_b32 s70, s6, 0x80
	s_ashr_i32 s71, s70, 31
	s_add_i32 s55, s7, 0x2000
	s_lshl_b64 s[70:71], s[70:71], 11
	s_add_u32 s70, s30, s70
	s_mov_b32 m0, s7
	s_addc_u32 s71, s31, s71
	s_bitset1_b32 s22, 7
	global_load_lds_dwordx4 v[2:3], off
	v_lshl_add_u64 v[4:5], v[2:3], 0, s[84:85]
	s_mov_b32 m0, s55
	s_ashr_i32 s23, s22, 31
	global_load_lds_dwordx4 v[4:5], off
	v_lshl_add_u64 v[4:5], s[70:71], 0, v[12:13]
	s_add_i32 s70, s7, 0x14000
	s_add_i32 s71, s7, 0x16000
	s_lshl_b64 s[22:23], s[22:23], 11
	s_mov_b32 m0, s70
	s_add_u32 s22, s26, s22
	global_load_lds_dwordx4 v[4:5], off
	v_lshl_add_u64 v[14:15], v[4:5], 0, s[84:85]
	s_mov_b32 m0, s71
	s_addc_u32 s23, s27, s23
	s_add_i32 s72, s7, 0x4000
	global_load_lds_dwordx4 v[14:15], off
	v_lshl_add_u64 v[128:129], s[22:23], 0, v[12:13]
	s_mov_b32 m0, s72
	s_add_i32 s73, s7, 0x6000
	global_load_lds_dwordx4 v[128:129], off
	v_lshl_add_u64 v[12:13], v[128:129], 0, s[84:85]
	s_mov_b32 m0, s73
	s_nop 0
	global_load_lds_dwordx4 v[12:13], off
	s_movk_i32 s14, 0x100
	v_cmp_gt_i32_e32 vcc, s14, v8
	s_movk_i32 s14, 0x4000
	v_cmp_gt_i32_e64 s[14:15], s14, v32
	s_and_b64 s[14:15], vcc, s[14:15]
	s_and_saveexec_b64 s[16:17], s[14:15]
	s_cbranch_execz .Lup_rstd_skip
	v_ashrrev_i32_e32 v33, 31, v32
	v_readlane_b32 s14, v255, 46
	v_lshlrev_b64 v[32:33], 6, v[32:33]
	v_readlane_b32 s15, v255, 47
	s_nop 1
	v_lshl_add_u64 v[36:37], s[14:15], 0, v[32:33]
	global_load_dwordx4 v[32:35], v[36:37], off
	global_load_dwordx4 v[42:45], v[36:37], off offset:16
	global_load_dwordx4 v[46:49], v[36:37], off offset:32
	global_load_dwordx4 v[50:53], v[36:37], off offset:48
	s_waitcnt vmcnt(3)
	v_mov_b32_e32 v36, v32
	s_waitcnt vmcnt(2)
	v_mov_b32_e32 v37, v42
	v_mov_b32_e32 v42, v33
	v_mov_b32_e32 v32, v34
	v_mov_b32_e32 v33, v44
	v_mov_b32_e32 v44, v35
	s_waitcnt vmcnt(1)
	v_mov_b32_e32 v34, v46
	s_waitcnt vmcnt(0)
	v_mov_b32_e32 v35, v50
	v_mov_b32_e32 v50, v47
	v_pk_add_f32 v[36:37], v[36:37], v[42:43]
	v_mov_b32_e32 v46, v48
	v_mov_b32_e32 v47, v52
	v_pk_add_f32 v[34:35], v[34:35], v[50:51]
	v_pk_add_f32 v[32:33], v[36:37], v[32:33]
	v_mov_b32_e32 v52, v49
	v_pk_add_f32 v[34:35], v[34:35], v[46:47]
	v_pk_add_f32 v[32:33], v[32:33], v[44:45]
	v_pk_add_f32 v[34:35], v[34:35], v[52:53]
	v_add_f32_e32 v32, v32, v33
	v_add_f32_e32 v32, v32, v34
	v_add_f32_e32 v32, v32, v35
	v_fmamk_f32 v32, v32, 0x3a800000, v194
	v_mul_f32_e32 v33, 0x4b800000, v32
	v_cmp_gt_f32_e32 vcc, s33, v32
	s_nop 1
	v_cndmask_b32_e32 v32, v32, v33, vcc
	v_rsq_f32_e32 v32, v32
	v_and_b32_e32 v33, 0xff, v8
	v_lshl_or_b32 v33, v33, 2, v195
	v_mul_f32_e32 v34, 0x45800000, v32
	v_cndmask_b32_e32 v32, v32, v34, vcc
	ds_write_b32 v33, v32
.Lup_rstd_skip:
	s_or_b64 exec, exec, s[16:17]
	s_cmp_lg_u32 s45, 1
	s_cbranch_scc1 .LBB0_467
	s_barrier
